# P6a: per-token vectors stored as whole 128-byte lines (first halves held in staging registers, lane exchange before the store)
# baseline (speedup 1.0000x reference)
; #define LAS __attribute__((address_space(3)))
; __device__ __forceinline__ void prep_rwkv_phase(const Params& p, LAS unsigned char* lds, int gw, int ngw, int wave, int lane) {
;     ...
;     for (int h = 0; h < 8; ++h) {
;         if (h < 7) prep_w_load(p, h + 1, tid, wreg);
;         if (active) {
;         {
;             f32x4 accG[4];
; #pragma unroll
;             for (int i = 0; i < 4; ++i) { accG[i] = (f32x4){0.f, 0.f, 0.f, 0.f};
; #pragma unroll
;                 for (int ks = 0; ks < 4; ++ks) {
;                     const bf16x8 wg = *(const LAS bf16x8*)(WG + (i * 16 + fr) * 136 + ks * 32 + fq * 8), ag = *(const LAS bf16x8*)(act + fr * 264 + 128 + ks * 32 + fq * 8);
;                     accG[i] = __builtin_amdgcn_mfma_f32_16x16x32_bf16(wg, ag, accG[i], 0, 0, 0); } }
; #pragma unroll
;             for (int hf = 0; hf < 2; ++hf)
;                 *(u32x4*)(G + (size_t)m * 512 + h * 64 + fq * 16 + hf * 8) = (u32x4){pk2(accG[2 * hf][0], accG[2 * hf][1]), pk2(accG[2 * hf][2], accG[2 * hf][3]), pk2(accG[2 * hf + 1][0], accG[2 * hf + 1][1]), pk2(accG[2 * hf + 1][2], accG[2 * hf + 1][3])};
;         }
;         f32x4 accD[4], accA[4];
; #pragma unroll
;         for (int i = 0; i < 4; ++i) {
;             accD[i] = (f32x4){0.f, 0.f, 0.f, 0.f}; accA[i] = accD[i];
; #pragma unroll
;             for (int ks = 0; ks < 2; ++ks) {
;                 const bf16x8 wd = *(const LAS bf16x8*)(WD + (i * 16 + fr) * 72 + ks * 32 + fq * 8), ad = *(const LAS bf16x8*)(act + fr * 264 + ks * 32 + fq * 8);
;                 accD[i] = __builtin_amdgcn_mfma_f32_16x16x32_bf16(wd, ad, accD[i], 0, 0, 0);
;                 const bf16x8 wa = *(const LAS bf16x8*)(WA + (i * 16 + fr) * 72 + ks * 32 + fq * 8), aa = *(const LAS bf16x8*)(act + fr * 264 + 64 + ks * 32 + fq * 8);
;                 accA[i] = __builtin_amdgcn_mfma_f32_16x16x32_bf16(wa, aa, accA[i], 0, 0, 0);
;             }
;         }
;         float nk = 0.f, sbr = 0.f, skr = 0.f, sbo = 0.f;
;         u32x4 kcs[2], kps[2];
; #pragma unroll
;         for (int hf = 0; hf < 2; ++hf) {
;             const int o_ = h * 64 + fq * 16 + hf * 8;
;             kcs[hf] = *(const u32x4*)(prow + 512 + o_); kps[hf] = *(const u32x4*)(pprev + 512 + o_); if (first) kps[hf] = (u32x4){0u, 0u, 0u, 0u};
;             const u32x4 kc = kcs[hf], kp = kps[hf];
; #pragma unroll
.LBB0_857:
	s_andn2_b64 vcc, exec, s[20:21]
	s_cbranch_vccnz .LBB0_861
	v_lshlrev_b32_e32 v96, 1, v144
	v_add_co_u32_e32 v94, vcc, v136, v96
	s_nop 1
	v_addc_co_u32_e32 v95, vcc, 0, v137, vcc
	global_load_dwordx4 v[98:101], v[94:95], off offset:1024
	global_load_dwordx4 v[102:105], v[94:95], off offset:1040
	global_load_dwordx4 v[106:109], v[94:95], off offset:2048
	global_load_dwordx4 v[110:113], v[94:95], off
	v_add_co_u32_e32 v94, vcc, v134, v96
	s_nop 1
	v_addc_co_u32_e32 v95, vcc, 0, v135, vcc
	global_load_dwordx4 v[114:117], v[94:95], off offset:1040
	global_load_dwordx4 v[122:125], v[94:95], off offset:2048
	global_load_dwordx4 v[126:129], v[94:95], off offset:1024
	global_load_dwordx4 v[240:243], v[94:95], off
	s_waitcnt lgkmcnt(1)
	ds_read_b128 v[20:23], v222
	ds_read_b128 v[24:27], v213 offset:256
	ds_read_b128 v[28:31], v222 offset:64
	ds_read_b128 v[32:35], v213 offset:320
	ds_read_b128 v[36:39], v222 offset:4352
	ds_read_b128 v[40:43], v222 offset:4416
	ds_read_b128 v[44:47], v222 offset:128
	ds_read_b128 v[48:51], v222 offset:192
	s_waitcnt lgkmcnt(6)
	v_mfma_f32_16x16x32_bf16 v[20:23], v[20:23], v[24:27], 0
	v_lshl_add_u64 v[0:1], s[92:93], 0, v[142:143]
	v_add_co_u32_e32 v0, vcc, s28, v0
	s_waitcnt lgkmcnt(4)
	v_mfma_f32_16x16x32_bf16 v[20:23], v[28:31], v[32:35], v[20:23]
	ds_read_b128 v[28:31], v213 offset:384
	ds_read_b128 v[52:55], v213 offset:448
	v_addc_co_u32_e32 v1, vcc, 0, v1, vcc
	s_waitcnt lgkmcnt(5)
	v_mfma_f32_16x16x32_bf16 v[36:39], v[36:39], v[24:27], 0
	v_ashrrev_i32_e32 v145, 31, v144
	v_add_u32_e32 v187, s31, v97
	v_add_u32_e32 v2, 0x11040, v187
	s_waitcnt lgkmcnt(1)
	v_mfma_f32_16x16x32_bf16 v[20:23], v[44:47], v[28:31], v[20:23]
	ds_read_b128 v[44:47], v222 offset:4480
	v_mfma_f32_16x16x32_bf16 v[36:39], v[40:43], v[32:35], v[36:39]
	ds_read_b128 v[40:43], v222 offset:4544
	s_waitcnt lgkmcnt(1)
	v_mfma_f32_16x16x32_bf16 v[36:39], v[44:47], v[28:31], v[36:39]
	ds_read_b128 v[44:47], v222 offset:8704
	s_waitcnt lgkmcnt(1)
	v_mfma_f32_16x16x32_bf16 v[36:39], v[40:43], v[52:55], v[36:39]
	ds_read_b128 v[40:43], v222 offset:8768
	v_mfma_f32_16x16x32_bf16 v[20:23], v[48:51], v[52:55], v[20:23]
	ds_read_b128 v[48:51], v222 offset:8832
	s_waitcnt lgkmcnt(2)
	v_mfma_f32_16x16x32_bf16 v[44:47], v[44:47], v[24:27], 0
	s_waitcnt lgkmcnt(1)
	v_mfma_f32_16x16x32_bf16 v[40:43], v[40:43], v[32:35], v[44:47]
	s_nop 2
	v_cvt_pk_bf16_f32 v20, v20, v21
	v_cvt_pk_bf16_f32 v21, v22, v23
	v_cvt_pk_bf16_f32 v22, v36, v37
	ds_read_b128 v[44:47], v222 offset:8896
	s_waitcnt lgkmcnt(1)
	v_mfma_f32_16x16x32_bf16 v[40:43], v[48:51], v[28:31], v[40:43]
	ds_read_b128 v[48:51], v222 offset:13056
	ds_read_b128 v[56:59], v222 offset:13120
	v_cvt_pk_bf16_f32 v23, v38, v39
	s_waitcnt lgkmcnt(1)
	v_mfma_f32_16x16x32_bf16 v[24:27], v[48:51], v[24:27], 0
	v_mfma_f32_16x16x32_bf16 v[40:43], v[44:47], v[52:55], v[40:43]
	ds_read_b128 v[44:47], v222 offset:13184
	ds_read_b128 v[60:63], v222 offset:13248
	global_store_dwordx4 v[0:1], v[20:23], off
	s_waitcnt lgkmcnt(2)
	v_mfma_f32_16x16x32_bf16 v[24:27], v[56:59], v[32:35], v[24:27]
	s_nop 2
	v_cvt_pk_bf16_f32 v20, v40, v41
	v_cvt_pk_bf16_f32 v21, v42, v43
	s_waitcnt lgkmcnt(1)
	v_mfma_f32_16x16x32_bf16 v[24:27], v[44:47], v[28:31], v[24:27]
	s_waitcnt lgkmcnt(0)
	v_mfma_f32_16x16x32_bf16 v[22:25], v[60:63], v[52:55], v[24:27]
	s_nop 7
	v_cvt_pk_bf16_f32 v22, v22, v23
	v_cvt_pk_bf16_f32 v23, v24, v25
	global_store_dwordx4 v[0:1], v[20:23], off offset:16
	v_lshlrev_b64 v[0:1], 1, v[144:145]
	v_lshl_add_u64 v[154:155], v[136:137], 0, v[0:1]
	s_nop 1
	s_waitcnt vmcnt(9)
	v_mov_b64_e32 v[20:21], v[98:99]
	v_mov_b64_e32 v[22:23], v[100:101]
	global_load_dwordx4 v[98:101], v[154:155], off offset:16
	ds_read_b128 v[24:27], v214
	ds_read_b128 v[28:31], v213
	s_nop 1
	s_waitcnt vmcnt(9)
	v_mov_b64_e32 v[32:33], v[102:103]
	v_mov_b64_e32 v[34:35], v[104:105]
	global_load_dwordx4 v[102:105], v[154:155], off offset:2064
	ds_read_b128 v[36:39], v215
	ds_read_b128 v[78:81], v213 offset:128
	ds_read_b128 v[40:43], v214 offset:64
	ds_read_b128 v[82:85], v213 offset:64
	s_waitcnt lgkmcnt(4)
	v_mfma_f32_16x16x32_bf16 v[24:27], v[24:27], v[28:31], 0
	v_lshl_add_u64 v[152:153], v[134:135], 0, v[0:1]
	ds_read_b128 v[44:47], v215 offset:64
	ds_read_b128 v[156:159], v213 offset:192
	s_nop 1
	s_waitcnt vmcnt(7)
	v_mov_b64_e32 v[168:169], v[114:115]
	v_mov_b64_e32 v[170:171], v[116:117]
	global_load_dwordx4 v[114:117], v[152:153], off offset:16
	s_waitcnt lgkmcnt(2)
	v_mfma_f32_16x16x32_bf16 v[90:93], v[40:43], v[82:85], v[24:27]
	v_add_u32_e32 v0, 0x11000, v187
	v_add_u32_e32 v1, 0x13000, v187
	s_nop 0
	v_cndmask_b32_e64 v228, v20, 0, s[6:7]
	ds_read_b128 v[24:27], v216
	v_mfma_f32_16x16x32_bf16 v[36:39], v[36:39], v[78:81], 0
	v_add_u32_e32 v20, 0x13080, v187
	v_cndmask_b32_e64 v130, v23, 0, s[6:7]
	v_cndmask_b32_e64 v151, v22, 0, s[6:7]
	s_waitcnt lgkmcnt(1)
	v_mfma_f32_16x16x32_bf16 v[86:89], v[44:47], v[156:159], v[36:39]
	s_nop 2
	ds_read_b128 v[36:39], v217
	ds_read_b128 v[40:43], v216 offset:64
	ds_read_b128 v[44:47], v217 offset:64
	ds_read_b128 v[54:57], v218
	ds_read_b128 v[58:61], v218 offset:64
	ds_read_b128 v[62:65], v219
	ds_read_b128 v[66:69], v219 offset:64
	ds_read_b128 v[160:163], v220
	ds_read_b128 v[164:167], v220 offset:64
	s_waitcnt lgkmcnt(9)
	v_mfma_f32_16x16x32_bf16 v[24:27], v[24:27], v[28:31], 0
	v_cndmask_b32_e64 v186, v21, 0, s[6:7]
	s_nop 0
	v_cndmask_b32_e64 v33, v33, 0, s[6:7]
	v_cndmask_b32_e64 v48, v35, 0, s[6:7]
	s_waitcnt lgkmcnt(7)
	v_mfma_f32_16x16x32_bf16 v[50:53], v[40:43], v[82:85], v[24:27]
	s_nop 2
	ds_read_b128 v[24:27], v221
	ds_read_b128 v[172:175], v221 offset:64
	s_nop 1
	s_waitcnt vmcnt(10)
; __device__ __forceinline__ void prep_rwkv_phase(const Params& p, LAS unsigned char* lds, int gw, int ngw, int wave, int lane) {
;     ...
;         f32x4 accD[4], accA[4];
; #pragma unroll
;         for (int i = 0; i < 4; ++i) {
;             accD[i] = (f32x4){0.f, 0.f, 0.f, 0.f}; accA[i] = accD[i];
; #pragma unroll
;             for (int ks = 0; ks < 2; ++ks) {
;                 const bf16x8 wd = *(const LAS bf16x8*)(WD + (i * 16 + fr) * 72 + ks * 32 + fq * 8), ad = *(const LAS bf16x8*)(act + fr * 264 + ks * 32 + fq * 8);
;                 accD[i] = __builtin_amdgcn_mfma_f32_16x16x32_bf16(wd, ad, accD[i], 0, 0, 0);
;                 const bf16x8 wa = *(const LAS bf16x8*)(WA + (i * 16 + fr) * 72 + ks * 32 + fq * 8), aa = *(const LAS bf16x8*)(act + fr * 264 + 64 + ks * 32 + fq * 8);
;                 accA[i] = __builtin_amdgcn_mfma_f32_16x16x32_bf16(wa, aa, accA[i], 0, 0, 0);
;             }
;         }
;         float nk = 0.f, sbr = 0.f, skr = 0.f, sbo = 0.f;
;         u32x4 kcs[2], kps[2];
; #pragma unroll
;         for (int hf = 0; hf < 2; ++hf) {
;             const int o_ = h * 64 + fq * 16 + hf * 8;
;             kcs[hf] = *(const u32x4*)(prow + 512 + o_); kps[hf] = *(const u32x4*)(pprev + 512 + o_); if (first) kps[hf] = (u32x4){0u, 0u, 0u, 0u};
;             const u32x4 kc = kcs[hf], kp = kps[hf];
; #pragma unroll
;             for (int i2 = 0; i2 < 2; ++i2) { const int c = h * 64 + (2 * hf + i2) * 16 + 4 * fq; const f32x4 muk = *(const LAS f32x4*)(PRM + 512 + c), kk4 = *(const LAS f32x4*)(PRM + 2560 + c);
; #pragma unroll
;                 for (int j = 0; j < 4; ++j) { const int e8 = i2 * 4 + j; const unsigned wc_ = kc[e8 >> 1], wp_ = kp[e8 >> 1];
;                     const float kcur = (e8 & 1) ? bfhi(wc_) : bflo(wc_), kprv = (e8 & 1) ? bfhi(wp_) : bflo(wp_); const float kr_ = (kcur + (kprv - kcur) * muk[j]) * kk4[j]; nk += kr_ * kr_; } }
;         }
;         nk += __shfl_xor(nk, 16); nk += __shfl_xor(nk, 32);
;         const float inv = 1.f / fmaxf(sqrtf(nk), 1e-12f);
;         h16* scp = SC + ((size_t)(b * 8 + h) * SEQ + tin) * 384 + fq * 16;
; #pragma unroll
;         for (int hf = 0; hf < 2; ++hf) {
;             h16x8 owr, odec, ok2, ov, okk, ob;
;             const int o_ = h * 64 + fq * 16 + hf * 8;
;             const u32x4 rc = *(const u32x4*)(prow + o_), kc = kcs[hf], vc = *(const u32x4*)(prow + 1024 + o_);
	v_mov_b64_e32 v[176:177], v[106:107]
	v_mov_b64_e32 v[178:179], v[108:109]
	global_load_dwordx4 v[106:109], v[152:153], off offset:2064
	s_nop 1
	s_waitcnt vmcnt(10)
	v_mov_b64_e32 v[180:181], v[110:111]
	v_mov_b64_e32 v[182:183], v[112:113]
	v_mfma_f32_16x16x32_bf16 v[36:39], v[36:39], v[78:81], 0
	s_nop 0
	v_and_b32_e32 v132, 0xffff0000, v171
	v_lshlrev_b32_e32 v185, 16, v168
	s_nop 0
	v_cndmask_b32_e64 v239, v182, 0, s[6:7]
	s_waitcnt lgkmcnt(8)
	v_mfma_f32_16x16x32_bf16 v[74:77], v[44:47], v[156:159], v[36:39]
	v_cndmask_b32_e64 v182, v181, 0, s[6:7]
	v_cndmask_b32_e64 v238, v183, 0, s[6:7]
	s_waitcnt lgkmcnt(7)
	v_mfma_f32_16x16x32_bf16 v[44:47], v[54:57], v[28:31], 0
	v_add_u32_e32 v36, 0x13040, v187
	s_waitcnt lgkmcnt(5)
	v_mfma_f32_16x16x32_bf16 v[70:73], v[62:65], v[78:81], 0
	ds_read_b128 v[188:191], v0
	ds_read_b128 v[40:43], v1
	ds_read_b128 v[62:65], v2
	ds_read_b128 v[36:39], v36
	v_add_u32_e32 v1, 0x11080, v187
	v_cndmask_b32_e64 v0, v32, 0, s[6:7]
	v_mfma_f32_16x16x32_bf16 v[54:57], v[58:61], v[82:85], v[44:47]
	v_lshlrev_b32_e32 v184, 16, v0
	v_and_b32_e32 v0, 0xffff0000, v0
	v_cndmask_b32_e64 v2, v34, 0, s[6:7]
	s_waitcnt lgkmcnt(8)
	v_mfma_f32_16x16x32_bf16 v[58:61], v[66:69], v[156:159], v[70:73]
	s_nop 2
	ds_read_b128 v[70:73], v1
	ds_read_b128 v[44:47], v20
	s_nop 1
	s_waitcnt vmcnt(8)
	v_mov_b64_e32 v[66:67], v[122:123]
	v_mov_b64_e32 v[68:69], v[124:125]
	v_and_b32_e32 v1, 0xffff0000, v169
	s_waitcnt lgkmcnt(9)
	v_mfma_f32_16x16x32_bf16 v[20:23], v[160:163], v[28:31], 0
	v_and_b32_e32 v161, 0xffff0000, v168
	v_sub_f32_e32 v0, v0, v161
	s_waitcnt lgkmcnt(1)
	v_fmac_f32_e32 v161, v71, v0
	v_mfma_f32_16x16x32_bf16 v[28:31], v[24:27], v[78:81], 0
	v_lshlrev_b32_e32 v0, 16, v169
	v_cndmask_b32_e64 v160, v177, 0, s[6:7]
	v_cndmask_b32_e64 v71, v178, 0, s[6:7]
	v_mfma_f32_16x16x32_bf16 v[24:27], v[164:167], v[82:85], v[20:23]
	s_nop 1
	s_waitcnt vmcnt(7)
	v_mov_b64_e32 v[78:79], v[126:127]
	v_mov_b64_e32 v[80:81], v[128:129]
	s_nop 1
	s_waitcnt vmcnt(6)
	v_mov_b64_e32 v[82:83], v[240:241]
	v_mov_b64_e32 v[84:85], v[242:243]
	s_nop 0
	v_and_b32_e32 v21, 0xffff0000, v33
	v_lshlrev_b32_e32 v20, 16, v33
	v_pk_add_f32 v[20:21], v[20:21], v[0:1] neg_lo:[0,1] neg_hi:[0,1]
	v_mfma_f32_16x16x32_bf16 v[28:31], v[172:175], v[156:159], v[28:31]
	v_fma_f32 v162, v72, v20, v0
	v_fma_f32 v163, v73, v21, v1
	v_add_u32_e32 v0, 0x110c0, v187
	v_add_u32_e32 v1, 0x130c0, v187
	ds_read_b128 v[32:35], v0
	ds_read_b128 v[20:23], v1
	s_waitcnt lgkmcnt(2)
	v_pk_mul_f32 v[158:159], v[46:47], v[162:163]
	v_and_b32_e32 v1, 0xffff0000, v170
	v_lshlrev_b32_e32 v0, 16, v170
	v_and_b32_e32 v47, 0xffff0000, v2
	v_lshlrev_b32_e32 v46, 16, v2
	v_pk_add_f32 v[46:47], v[46:47], v[0:1] neg_lo:[0,1] neg_hi:[0,1]
	v_lshlrev_b32_e32 v172, 16, v171
	s_waitcnt lgkmcnt(1)
	v_pk_fma_f32 v[164:165], v[32:33], v[46:47], v[0:1]
	v_lshlrev_b32_e32 v0, 16, v48
	v_sub_f32_e32 v0, v0, v172
	v_add_u32_e32 v32, 0x12000, v187
	v_mul_f32_e32 v150, v34, v0
	v_and_b32_e32 v0, 0xffff0000, v48
	ds_read_b128 v[46:49], v32
	v_add_u32_e32 v34, 0x12800, v187
	v_cndmask_b32_e64 v173, v176, 0, s[6:7]
	ds_read_b128 v[174:177], v34
	v_add_u32_e32 v32, 0x10800, v187
	s_waitcnt lgkmcnt(1)
	v_add_f32_e32 v34, v90, v46
	v_mul_f32_e32 v34, 0xbfb8aa3b, v34
	v_exp_f32_e32 v34, v34
	v_add_u32_e32 v33, 0x11800, v187
	ds_read_b128 v[192:195], v32
	ds_read_b128 v[196:199], v33
	s_waitcnt lgkmcnt(2)
	v_add_f32_e32 v72, v86, v174
	v_add_f32_e32 v33, 1.0, v34
	v_rcp_f32_e32 v46, v33
	v_mul_f32_e32 v72, 0xbfb8aa3b, v72
	v_add_f32_e32 v47, v91, v47
	v_exp_f32_e32 v72, v72
	v_mul_f32_e32 v47, 0xbfb8aa3b, v47
	v_exp_f32_e32 v47, v47
	v_mul_f32_e32 v46, 0xbf1b4598, v46
	v_mul_f32_e32 v46, 0x3fb8aa3b, v46
	v_cndmask_b32_e64 v73, v180, 0, s[6:7]
	v_exp_f32_e32 v180, v46
	v_add_f32_e32 v46, 1.0, v72
	v_rcp_f32_e32 v170, v46
	v_add_f32_e32 v46, 1.0, v47
	v_rcp_f32_e32 v46, v46
	v_add_f32_e32 v47, v87, v175
	v_mul_f32_e32 v47, 0xbfb8aa3b, v47
	v_exp_f32_e32 v47, v47
	v_mul_f32_e32 v46, 0xbf1b4598, v46
	v_mul_f32_e32 v46, 0x3fb8aa3b, v46
	v_exp_f32_e32 v181, v46
	v_add_f32_e32 v46, 1.0, v47
	v_rcp_f32_e32 v171, v46
	v_lshlrev_b32_e32 v72, 16, v73
	v_and_b32_e32 v73, 0xffff0000, v73
	v_sub_f32_e32 v0, v0, v132
	v_add_u32_e32 v32, 0x13800, v187
	v_add_u32_e32 v33, 0x14000, v187
	v_pk_mul_f32 v[156:157], v[20:21], v[164:165]
	v_mul_f32_e32 v20, v35, v0
	ds_read_b128 v[200:203], v32
	ds_read_b128 v[32:35], v33
	v_lshlrev_b32_e32 v90, 16, v228
	v_and_b32_e32 v91, 0xffff0000, v228
	v_cndmask_b32_e64 v21, v179, 0, s[6:7]
	v_lshlrev_b32_e32 v174, 16, v173
	v_and_b32_e32 v175, 0xffff0000, v173
	v_and_b32_e32 v1, 64, v227
	v_xor_b32_e32 v0, 16, v227
	v_add_u32_e32 v1, 64, v1
	v_cmp_lt_i32_e32 vcc, v0, v1
	v_pk_mul_f32 v[166:167], v[158:159], v[158:159]
	v_mov_b32_e32 v173, v133
	v_cndmask_b32_e32 v0, v227, v0, vcc
	v_lshlrev_b32_e32 v145, 2, v0
	v_xor_b32_e32 v0, 32, v227
	v_cmp_lt_i32_e32 vcc, v0, v1
	s_nop 0
	v_lshlrev_b32_e32 v46, 16, v82
	v_and_b32_e32 v47, 0xffff0000, v82
	v_pk_add_f32 v[72:73], v[72:73], v[46:47] neg_lo:[0,1] neg_hi:[0,1]
	v_cndmask_b32_e32 v0, v227, v0, vcc
	s_waitcnt lgkmcnt(3)
	v_pk_fma_f32 v[86:87], v[192:193], v[72:73], v[46:47]
	v_lshlrev_b32_e32 v2, 2, v0
	v_pk_mul_f32 v[46:47], v[86:87], v[180:181]
	v_lshl_add_u64 v[0:1], s[92:93], 0, v[140:141]
	v_cvt_pk_f16_f32 v72, v46, v47
	v_lshlrev_b32_e32 v46, 16, v78
	v_and_b32_e32 v47, 0xffff0000, v78
	v_pk_add_f32 v[90:91], v[90:91], v[46:47] neg_lo:[0,1] neg_hi:[0,1]
	v_pk_mul_f32 v[168:169], v[156:157], v[156:157]
	v_pk_fma_f32 v[178:179], v[188:189], v[90:91], v[46:47]
	v_pk_add_f32 v[46:47], v[170:171], -1.0 op_sel_hi:[1,0]
	s_waitcnt lgkmcnt(1)
; #define LAS __attribute__((address_space(3)))
; __device__ __forceinline__ float fast_sigmoid(float x) { return __builtin_amdgcn_rcpf(1.f + __expf(-x)); }
; __device__ __forceinline__ void prep_rwkv_phase(const Params& p, LAS unsigned char* lds, int gw, int ngw, int wave, int lane) {
;     ...
;         for (int hf = 0; hf < 2; ++hf) {
;             h16x8 owr, odec, ok2, ov, okk, ob;
;             const int o_ = h * 64 + fq * 16 + hf * 8;
;             const u32x4 rc = *(const u32x4*)(prow + o_), kc = kcs[hf], vc = *(const u32x4*)(prow + 1024 + o_);
;             u32x4 rp = *(const u32x4*)(pprev + o_), vp = *(const u32x4*)(pprev + 1024 + o_); const u32x4 kp = kps[hf];
;             if (first) { rp = (u32x4){0u, 0u, 0u, 0u}; vp = rp; }
; #pragma unroll
;             for (int i2 = 0; i2 < 2; ++i2) {
;                 const int i = 2 * hf + i2, c = h * 64 + i * 16 + 4 * fq;
;                 const f32x4 mur = *(const LAS f32x4*)(PRM + c), muk = *(const LAS f32x4*)(PRM + 512 + c), muv = *(const LAS f32x4*)(PRM + 1024 + c);
;                 const f32x4 w04 = *(const LAS f32x4*)(PRM + 1536 + c), a04 = *(const LAS f32x4*)(PRM + 2048 + c), kk4 = *(const LAS f32x4*)(PRM + 2560 + c), ka4 = *(const LAS f32x4*)(PRM + 3072 + c), rk4 = *(const LAS f32x4*)(PRM + 3584 + c);
; #pragma unroll
;                 for (int j = 0; j < 4; ++j) {
;                     const int e8 = i2 * 4 + j, e = hf * 8 + e8; const unsigned wsel = (e8 >> 1); const bool hiw = e8 & 1;
;     ...
;                     const float rcur = PREP_GET(rc), rprv = PREP_GET(rp), kcur = PREP_GET(kc), kprv = PREP_GET(kp), vcur = PREP_GET(vc), vprv = PREP_GET(vp);
;     ...
;                     const float r = rcur + (rprv - rcur) * mur[j], k = kcur + (kprv - kcur) * muk[j], v = vcur + (vprv - vcur) * muv[j];
;                     const float dec = __expf(-0.60653066f * fast_sigmoid(w04[j] + accD[i][j]));
;                     const float a = fast_sigmoid(a04[j] + accA[i][j]);
;                     const float kraw = k * kk4[j], k2 = k * (1.f + (a - 1.f) * ka4[j]);
;                     const float kkn = kraw * inv, bn = kkn * a; sbr += bn * r; skr += k2 * r; sbo += r * k2 * rk4[j];
;                     okk[e8] = (h16)kkn; ob[e8] = (h16)bn;
;                     owr[e8] = (h16)(dec * r); odec[e8] = (h16)dec; ok2[e8] = (h16)k2; ov[e8] = (h16)v;
;                 }
;             }
	v_pk_fma_f32 v[46:47], v[200:201], v[46:47], 1.0 op_sel_hi:[1,1,0]
	s_nop 0
	v_pk_mul_f32 v[90:91], v[178:179], v[46:47]
	v_add_f32_e32 v47, v92, v48
	v_mul_f32_e32 v47, 0xbfb8aa3b, v47
	v_exp_f32_e32 v48, v47
	v_lshlrev_b32_e32 v46, 16, v66
	v_and_b32_e32 v47, 0xffff0000, v66
	v_pk_add_f32 v[174:175], v[174:175], v[46:47] neg_lo:[0,1] neg_hi:[0,1]
	v_add_f32_e32 v48, 1.0, v48
	v_rcp_f32_e32 v48, v48
	v_pk_fma_f32 v[46:47], v[196:197], v[174:175], v[46:47]
	v_lshlrev_b32_e32 v174, 16, v80
	v_cvt_pk_f16_f32 v66, v46, v47
	v_add_f32_e32 v47, v88, v176
	v_mul_f32_e32 v46, 0xbf1b4598, v48
	v_mul_f32_e32 v47, 0xbfb8aa3b, v47
	v_add_f32_e32 v48, v93, v49
	v_exp_f32_e32 v47, v47
	v_mul_f32_e32 v48, 0xbfb8aa3b, v48
	v_exp_f32_e32 v48, v48
	v_mul_f32_e32 v46, 0x3fb8aa3b, v46
	v_exp_f32_e32 v236, v46
	v_add_f32_e32 v46, 1.0, v47
	v_rcp_f32_e32 v176, v46
	v_add_f32_e32 v46, 1.0, v48
	v_rcp_f32_e32 v46, v46
	v_add_f32_e32 v47, v89, v177
	v_mul_f32_e32 v47, 0xbfb8aa3b, v47
	v_exp_f32_e32 v47, v47
	v_mul_f32_e32 v46, 0xbf1b4598, v46
	v_mul_f32_e32 v46, 0x3fb8aa3b, v46
	v_exp_f32_e32 v237, v46
	v_add_f32_e32 v46, 1.0, v47
	v_rcp_f32_e32 v177, v46
	v_lshlrev_b32_e32 v46, 16, v83
	v_and_b32_e32 v47, 0xffff0000, v83
	v_lshlrev_b32_e32 v48, 16, v182
	v_and_b32_e32 v49, 0xffff0000, v182
	v_pk_add_f32 v[48:49], v[48:49], v[46:47] neg_lo:[0,1] neg_hi:[0,1]
	v_and_b32_e32 v175, 0xffff0000, v80
	v_pk_fma_f32 v[82:83], v[194:195], v[48:49], v[46:47]
	v_lshlrev_b32_e32 v48, 16, v186
	v_pk_mul_f32 v[46:47], v[82:83], v[236:237]
	v_and_b32_e32 v49, 0xffff0000, v186
	v_cvt_pk_f16_f32 v73, v46, v47
	v_lshlrev_b32_e32 v46, 16, v79
	v_and_b32_e32 v47, 0xffff0000, v79
	v_pk_add_f32 v[48:49], v[48:49], v[46:47] neg_lo:[0,1] neg_hi:[0,1]
	v_lshlrev_b32_e32 v92, 16, v239
	v_pk_fma_f32 v[188:189], v[190:191], v[48:49], v[46:47]
	v_pk_add_f32 v[46:47], v[176:177], -1.0 op_sel_hi:[1,0]
	v_lshlrev_b32_e32 v48, 16, v160
	v_pk_fma_f32 v[46:47], v[202:203], v[46:47], 1.0 op_sel_hi:[1,1,0]
	v_and_b32_e32 v49, 0xffff0000, v160
	v_pk_mul_f32 v[88:89], v[188:189], v[46:47]
	v_lshlrev_b32_e32 v46, 16, v67
	v_and_b32_e32 v47, 0xffff0000, v67
	v_pk_add_f32 v[48:49], v[48:49], v[46:47] neg_lo:[0,1] neg_hi:[0,1]
	v_and_b32_e32 v93, 0xffff0000, v239
	v_pk_fma_f32 v[46:47], v[198:199], v[48:49], v[46:47]
	v_add_u32_e32 v48, 0x12840, v187
	v_cvt_pk_f16_f32 v67, v46, v47
	v_add_u32_e32 v46, 0x12040, v187
	ds_read_b128 v[190:193], v46
	ds_read_b128 v[194:197], v48
	v_add_u32_e32 v46, 0x10840, v187
	v_add_u32_e32 v47, 0x11840, v187
	ds_read_b128 v[198:201], v46
	ds_read_b128 v[228:231], v47
	s_waitcnt lgkmcnt(3)
	v_add_f32_e32 v48, v50, v190
	s_waitcnt lgkmcnt(2)
	v_add_f32_e32 v74, v74, v194
	v_mul_f32_e32 v74, 0xbfb8aa3b, v74
	v_exp_f32_e32 v74, v74
	v_mul_f32_e32 v48, 0xbfb8aa3b, v48
	v_exp_f32_e32 v48, v48
	v_add_u32_e32 v46, 0x13840, v187
	v_add_f32_e32 v74, 1.0, v74
	v_rcp_f32_e32 v182, v74
	v_add_f32_e32 v74, v75, v195
	v_mul_f32_e32 v74, 0xbfb8aa3b, v74
	v_exp_f32_e32 v74, v74
	v_add_f32_e32 v47, 1.0, v48
	v_rcp_f32_e32 v50, v47
	v_add_u32_e32 v47, 0x14040, v187
	v_add_f32_e32 v74, 1.0, v74
	v_rcp_f32_e32 v183, v74
	ds_read_b128 v[232:235], v46
	ds_read_b128 v[46:49], v47
	v_add_f32_e32 v51, v51, v191
	v_lshlrev_b32_e32 v190, 16, v151
	v_and_b32_e32 v191, 0xffff0000, v151
	v_pk_add_f32 v[190:191], v[190:191], v[174:175] neg_lo:[0,1] neg_hi:[0,1]
	v_add_f32_e32 v52, v52, v192
	v_pk_fma_f32 v[202:203], v[62:63], v[190:191], v[174:175]
	v_pk_add_f32 v[62:63], v[182:183], -1.0 op_sel_hi:[1,0]
	v_lshlrev_b32_e32 v190, 16, v71
	s_waitcnt lgkmcnt(1)
	v_pk_fma_f32 v[62:63], v[232:233], v[62:63], 1.0 op_sel_hi:[1,1,0]
	v_and_b32_e32 v191, 0xffff0000, v71
	v_pk_mul_f32 v[174:175], v[202:203], v[62:63]
	v_lshlrev_b32_e32 v62, 16, v68
	v_and_b32_e32 v63, 0xffff0000, v68
	v_pk_add_f32 v[190:191], v[190:191], v[62:63] neg_lo:[0,1] neg_hi:[0,1]
	v_add_f32_e32 v53, v53, v193
	v_pk_fma_f32 v[62:63], v[190:191], v[228:229], v[62:63]
	v_mul_f32_e32 v51, 0xbfb8aa3b, v51
	v_cvt_pk_f16_f32 v68, v62, v63
	v_add_f32_e32 v62, v76, v196
	v_mul_f32_e32 v52, 0xbfb8aa3b, v52
	v_mul_f32_e32 v62, 0xbfb8aa3b, v62
	v_mul_f32_e32 v53, 0xbfb8aa3b, v53
	v_exp_f32_e32 v51, v51
	v_exp_f32_e32 v52, v52
	v_exp_f32_e32 v62, v62
	v_exp_f32_e32 v53, v53
	v_add_f32_e32 v51, 1.0, v51
	v_add_f32_e32 v52, 1.0, v52
	v_add_f32_e32 v62, 1.0, v62
	v_add_f32_e32 v53, 1.0, v53
	v_rcp_f32_e32 v51, v51
	v_rcp_f32_e32 v52, v52
	v_rcp_f32_e32 v196, v62
	v_rcp_f32_e32 v53, v53
	v_add_f32_e32 v62, v77, v197
	v_mul_f32_e32 v62, 0xbfb8aa3b, v62
	v_exp_f32_e32 v62, v62
	v_mul_f32_e32 v50, 0xbf1b4598, v50
	v_mul_f32_e32 v51, 0xbf1b4598, v51
	v_mul_f32_e32 v52, 0xbf1b4598, v52
	v_mul_f32_e32 v53, 0xbf1b4598, v53
	v_mul_f32_e32 v50, 0x3fb8aa3b, v50
	v_mul_f32_e32 v51, 0x3fb8aa3b, v51
	v_mul_f32_e32 v52, 0x3fb8aa3b, v52
	v_mul_f32_e32 v53, 0x3fb8aa3b, v53
	v_exp_f32_e32 v50, v50
	v_exp_f32_e32 v51, v51
	v_exp_f32_e32 v52, v52
	v_exp_f32_e32 v53, v53
	v_add_f32_e32 v62, 1.0, v62
	v_lshlrev_b32_e32 v74, 16, v84
	v_and_b32_e32 v75, 0xffff0000, v84
	v_rcp_f32_e32 v197, v62
	v_lshlrev_b32_e32 v62, 16, v85
	v_and_b32_e32 v63, 0xffff0000, v85
	v_lshlrev_b32_e32 v76, 16, v238
	v_and_b32_e32 v77, 0xffff0000, v238
	v_pk_add_f32 v[92:93], v[92:93], v[74:75] neg_lo:[0,1] neg_hi:[0,1]
	v_pk_add_f32 v[76:77], v[76:77], v[62:63] neg_lo:[0,1] neg_hi:[0,1]
	v_pk_fma_f32 v[92:93], v[92:93], v[198:199], v[74:75]
	v_pk_fma_f32 v[84:85], v[76:77], v[200:201], v[62:63]
	v_pk_mul_f32 v[74:75], v[92:93], v[50:51]
	v_pk_mul_f32 v[62:63], v[84:85], v[52:53]
	v_cvt_pk_f16_f32 v74, v74, v75
	v_cvt_pk_f16_f32 v75, v62, v63
	v_lshlrev_b32_e32 v62, 16, v81
	v_and_b32_e32 v63, 0xffff0000, v81
; #define LAS __attribute__((address_space(3)))
; __device__ __forceinline__ float fast_sigmoid(float x) { return __builtin_amdgcn_rcpf(1.f + __expf(-x)); }
; __device__ __forceinline__ void prep_rwkv_phase(const Params& p, LAS unsigned char* lds, int gw, int ngw, int wave, int lane) {
;     ...
;         for (int hf = 0; hf < 2; ++hf) {
;             h16x8 owr, odec, ok2, ov, okk, ob;
;             const int o_ = h * 64 + fq * 16 + hf * 8;
;             const u32x4 rc = *(const u32x4*)(prow + o_), kc = kcs[hf], vc = *(const u32x4*)(prow + 1024 + o_);
;             u32x4 rp = *(const u32x4*)(pprev + o_), vp = *(const u32x4*)(pprev + 1024 + o_); const u32x4 kp = kps[hf];
;             if (first) { rp = (u32x4){0u, 0u, 0u, 0u}; vp = rp; }
; #pragma unroll
;             for (int i2 = 0; i2 < 2; ++i2) {
;                 const int i = 2 * hf + i2, c = h * 64 + i * 16 + 4 * fq;
;                 const f32x4 mur = *(const LAS f32x4*)(PRM + c), muk = *(const LAS f32x4*)(PRM + 512 + c), muv = *(const LAS f32x4*)(PRM + 1024 + c);
;                 const f32x4 w04 = *(const LAS f32x4*)(PRM + 1536 + c), a04 = *(const LAS f32x4*)(PRM + 2048 + c), kk4 = *(const LAS f32x4*)(PRM + 2560 + c), ka4 = *(const LAS f32x4*)(PRM + 3072 + c), rk4 = *(const LAS f32x4*)(PRM + 3584 + c);
; #pragma unroll
;                 for (int j = 0; j < 4; ++j) {
;                     const int e8 = i2 * 4 + j, e = hf * 8 + e8; const unsigned wsel = (e8 >> 1); const bool hiw = e8 & 1;
;     ...
;                     const float rcur = PREP_GET(rc), rprv = PREP_GET(rp), kcur = PREP_GET(kc), kprv = PREP_GET(kp), vcur = PREP_GET(vc), vprv = PREP_GET(vp);
;     ...
;                     const float r = rcur + (rprv - rcur) * mur[j], k = kcur + (kprv - kcur) * muk[j], v = vcur + (vprv - vcur) * muv[j];
;                     const float dec = __expf(-0.60653066f * fast_sigmoid(w04[j] + accD[i][j]));
;                     const float a = fast_sigmoid(a04[j] + accA[i][j]);
;                     const float kraw = k * kk4[j], k2 = k * (1.f + (a - 1.f) * ka4[j]);
;                     const float kkn = kraw * inv, bn = kkn * a; sbr += bn * r; skr += k2 * r; sbo += r * k2 * rk4[j];
;                     okk[e8] = (h16)kkn; ob[e8] = (h16)bn;
;                     owr[e8] = (h16)(dec * r); odec[e8] = (h16)dec; ok2[e8] = (h16)k2; ov[e8] = (h16)v;
;                 }
;             }
	v_lshlrev_b32_e32 v76, 16, v130
	v_and_b32_e32 v77, 0xffff0000, v130
	v_pk_add_f32 v[76:77], v[76:77], v[62:63] neg_lo:[0,1] neg_hi:[0,1]
	v_cvt_pk_f16_f32 v53, v52, v53
	v_pk_fma_f32 v[232:233], v[64:65], v[76:77], v[62:63]
	v_pk_add_f32 v[62:63], v[196:197], -1.0 op_sel_hi:[1,0]
	v_cvt_pk_f16_f32 v52, v50, v51
	v_pk_fma_f32 v[62:63], v[234:235], v[62:63], 1.0 op_sel_hi:[1,1,0]
	v_cvt_pk_f16_f32 v50, v180, v181
	v_pk_mul_f32 v[180:181], v[232:233], v[62:63]
	v_lshlrev_b32_e32 v62, 16, v69
	v_and_b32_e32 v63, 0xffff0000, v69
	v_lshlrev_b32_e32 v64, 16, v21
	v_and_b32_e32 v65, 0xffff0000, v21
	v_pk_add_f32 v[64:65], v[64:65], v[62:63] neg_lo:[0,1] neg_hi:[0,1]
	v_cvt_pk_f16_f32 v78, v90, v91
	v_pk_fma_f32 v[62:63], v[64:65], v[230:231], v[62:63]
	v_cvt_pk_f16_f32 v79, v88, v89
	v_cvt_pk_f16_f32 v80, v174, v175
	v_cvt_pk_f16_f32 v51, v236, v237
	v_cvt_pk_f16_f32 v81, v180, v181
	v_cvt_pk_f16_f32 v69, v62, v63
	v_mov_b64_e32 v[110:111], v[72:73]
	v_mov_b64_e32 v[112:113], v[74:75]
	v_mov_b64_e32 v[122:123], v[50:51]
	v_mov_b64_e32 v[124:125], v[52:53]
	v_mov_b64_e32 v[126:127], v[78:79]
	v_mov_b64_e32 v[128:129], v[80:81]
	v_mov_b64_e32 v[240:241], v[66:67]
	v_mov_b64_e32 v[242:243], v[68:69]
	v_add_u32_e32 v21, 0x12080, v187
	ds_read_b128 v[72:75], v21
	v_add_u32_e32 v51, 0x12880, v187
	ds_read_b128 v[78:81], v51
	v_add_u32_e32 v21, 0x10880, v187
	v_add_u32_e32 v50, 0x11880, v187
	s_waitcnt lgkmcnt(1)
	v_add_f32_e32 v51, v54, v72
	v_mul_f32_e32 v51, 0xbfb8aa3b, v51
	v_exp_f32_e32 v54, v51
	s_waitcnt lgkmcnt(0)
	v_add_f32_e32 v58, v58, v78
	v_mul_f32_e32 v58, 0xbfb8aa3b, v58
	v_exp_f32_e32 v58, v58
	v_add_f32_e32 v54, 1.0, v54
	v_rcp_f32_e32 v54, v54
	ds_read_b128 v[62:65], v21
	ds_read_b128 v[50:53], v50
	v_add_u32_e32 v21, 0x13880, v187
	v_add_u32_e32 v66, 0x14080, v187
	ds_read_b128 v[228:231], v21
	ds_read_b128 v[66:69], v66
	v_add_f32_e32 v21, 1.0, v58
	v_rcp_f32_e32 v186, v21
	v_mul_f32_e32 v21, 0xbf1b4598, v54
	v_mov_b32_e32 v54, v185
	v_pk_add_f32 v[76:77], v[184:185], v[54:55] neg_lo:[0,1] neg_hi:[0,1]
	v_add_f32_e32 v54, v59, v79
	v_mul_f32_e32 v21, 0x3fb8aa3b, v21
	v_mul_f32_e32 v54, 0xbfb8aa3b, v54
	v_exp_f32_e32 v78, v21
	v_add_f32_e32 v21, -1.0, v186
	v_exp_f32_e32 v54, v54
	v_mov_b32_e32 v77, v21
	v_add_f32_e32 v21, v55, v73
	v_mul_f32_e32 v21, 0xbfb8aa3b, v21
	v_exp_f32_e32 v21, v21
	v_add_f32_e32 v54, 1.0, v54
	v_rcp_f32_e32 v160, v54
	v_add_f32_e32 v54, v56, v74
	v_mul_f32_e32 v54, 0xbfb8aa3b, v54
	v_add_f32_e32 v21, 1.0, v21
	v_exp_f32_e32 v54, v54
	v_rcp_f32_e32 v21, v21
	v_add_f32_e32 v55, v60, v80
	v_mul_f32_e32 v55, 0xbfb8aa3b, v55
	v_exp_f32_e32 v55, v55
	v_add_f32_e32 v54, 1.0, v54
	v_mul_f32_e32 v21, 0xbf1b4598, v21
	v_rcp_f32_e32 v54, v54
	v_mul_f32_e32 v21, 0x3fb8aa3b, v21
	v_exp_f32_e32 v79, v21
	v_add_f32_e32 v21, -1.0, v160
	s_waitcnt lgkmcnt(1)
	v_fma_f32 v201, v229, v21, 1.0
	v_add_f32_e32 v21, 1.0, v55
	v_rcp_f32_e32 v184, v21
	v_mul_f32_e32 v21, 0xbf1b4598, v54
	v_add_f32_e32 v54, v57, v75
	v_mul_f32_e32 v54, 0xbfb8aa3b, v54
	v_exp_f32_e32 v54, v54
	v_add_f32_e32 v55, v61, v81
	v_mul_f32_e32 v55, 0xbfb8aa3b, v55
	v_exp_f32_e32 v55, v55
	v_add_f32_e32 v54, 1.0, v54
	v_rcp_f32_e32 v54, v54
	v_mul_f32_e32 v21, 0x3fb8aa3b, v21
	v_exp_f32_e32 v80, v21
	v_add_f32_e32 v21, -1.0, v184
	v_fma_f32 v195, v230, v21, 1.0
	v_add_f32_e32 v21, 1.0, v55
	v_rcp_f32_e32 v190, v21
	v_mul_f32_e32 v21, 0xbf1b4598, v54
	v_mul_f32_e32 v21, 0x3fb8aa3b, v21
	v_mov_b32_e32 v71, v228
	v_mov_b32_e32 v130, v185
	v_exp_f32_e32 v81, v21
	v_add_u32_e32 v21, 0x120c0, v187
	v_pk_fma_f32 v[192:193], v[70:71], v[76:77], v[130:131]
	v_add_u32_e32 v54, 0x128c0, v187
	ds_read_b128 v[70:73], v21
	ds_read_b128 v[74:77], v54
	v_add_u32_e32 v21, 0x138c0, v187
	v_add_u32_e32 v54, 0x140c0, v187
	ds_read_b128 v[58:61], v21
	ds_read_b128 v[54:57], v54
	s_waitcnt lgkmcnt(3)
	v_add_f32_e32 v21, v24, v70
	v_mul_f32_e32 v24, 0xbfb8aa3b, v21
	s_waitcnt lgkmcnt(2)
	v_add_f32_e32 v21, v31, v77
	v_add_f32_e32 v30, v30, v76
	v_pk_mul_f32 v[228:229], v[40:41], v[178:179]
	v_mul_f32_e32 v21, 0xbfb8aa3b, v21
	v_mul_f32_e32 v30, 0xbfb8aa3b, v30
	v_pk_mul_f32 v[40:41], v[228:229], v[228:229]
	v_pk_mul_f32 v[188:189], v[42:43], v[188:189]
	v_exp_f32_e32 v21, v21
	v_exp_f32_e32 v30, v30
	v_pk_mul_f32 v[42:43], v[188:189], v[188:189]
	v_add_f32_e32 v40, v40, v41
	v_pk_mul_f32 v[202:203], v[36:37], v[202:203]
	v_add_f32_e32 v40, v42, v40
	v_pk_mul_f32 v[36:37], v[202:203], v[202:203]
	v_add_f32_e32 v40, v43, v40
	v_pk_mul_f32 v[232:233], v[38:39], v[232:233]
	v_add_f32_e32 v36, v36, v40
	v_add_f32_e32 v21, 1.0, v21
	v_add_f32_e32 v30, 1.0, v30
	v_pk_mul_f32 v[38:39], v[232:233], v[232:233]
	v_mov_b32_e32 v178, v192
	v_mov_b32_e32 v179, v161
	v_add_f32_e32 v36, v37, v36
	v_rcp_f32_e32 v21, v21
	v_rcp_f32_e32 v151, v30
	v_pk_mul_f32 v[178:179], v[44:45], v[178:179]
	v_add_f32_e32 v36, v38, v36
	v_pk_mul_f32 v[234:235], v[178:179], v[178:179]
	v_add_f32_e32 v36, v39, v36
	v_add_f32_e32 v36, v234, v36
	v_add_f32_e32 v36, v235, v36
	v_pk_add_f32 v[30:31], v[20:21], v[132:133]
	v_mov_b32_e32 v76, v23
	s_waitcnt lgkmcnt(1)
	v_mov_b32_e32 v77, v61
	v_pk_add_f32 v[44:45], v[150:151], v[172:173]
	v_mov_b32_e32 v23, v60
	v_add_f32_e32 v36, v166, v36
	v_pk_mul_f32 v[198:199], v[76:77], v[30:31]
	v_pk_mul_f32 v[60:61], v[22:23], v[44:45]
	v_add_f32_e32 v36, v167, v36
	v_mov_b32_e32 v172, v198
	v_mov_b32_e32 v173, v60
	v_add_f32_e32 v36, v168, v36
	v_pk_mul_f32 v[172:173], v[172:173], v[172:173]
	v_add_f32_e32 v36, v169, v36
	v_add_f32_e32 v36, v173, v36
	v_add_f32_e32 v36, v172, v36
	ds_bpermute_b32 v37, v145, v36
	v_exp_f32_e32 v24, v24
	v_add_f32_e32 v28, v28, v74
	v_mul_f32_e32 v28, 0xbfb8aa3b, v28
	v_exp_f32_e32 v28, v28
	s_waitcnt lgkmcnt(0)
; __device__ __forceinline__ void prep_rwkv_phase(const Params& p, LAS unsigned char* lds, int gw, int ngw, int wave, int lane) {
;     ...
;         float nk = 0.f, sbr = 0.f, skr = 0.f, sbo = 0.f;
;         u32x4 kcs[2], kps[2];
; #pragma unroll
;         for (int hf = 0; hf < 2; ++hf) {
;             const int o_ = h * 64 + fq * 16 + hf * 8;
;             kcs[hf] = *(const u32x4*)(prow + 512 + o_); kps[hf] = *(const u32x4*)(pprev + 512 + o_); if (first) kps[hf] = (u32x4){0u, 0u, 0u, 0u};
;             const u32x4 kc = kcs[hf], kp = kps[hf];
; #pragma unroll
;             for (int i2 = 0; i2 < 2; ++i2) { const int c = h * 64 + (2 * hf + i2) * 16 + 4 * fq; const f32x4 muk = *(const LAS f32x4*)(PRM + 512 + c), kk4 = *(const LAS f32x4*)(PRM + 2560 + c);
; #pragma unroll
;                 for (int j = 0; j < 4; ++j) { const int e8 = i2 * 4 + j; const unsigned wc_ = kc[e8 >> 1], wp_ = kp[e8 >> 1];
;                     const float kcur = (e8 & 1) ? bfhi(wc_) : bflo(wc_), kprv = (e8 & 1) ? bfhi(wp_) : bflo(wp_); const float kr_ = (kcur + (kprv - kcur) * muk[j]) * kk4[j]; nk += kr_ * kr_; } }
;         }
;         nk += __shfl_xor(nk, 16); nk += __shfl_xor(nk, 32);
;         const float inv = 1.f / fmaxf(sqrtf(nk), 1e-12f);
;         h16* scp = SC + ((size_t)(b * 8 + h) * SEQ + tin) * 384 + fq * 16;
; #pragma unroll
;         for (int hf = 0; hf < 2; ++hf) {
;             h16x8 owr, odec, ok2, ov, okk, ob;
;             const int o_ = h * 64 + fq * 16 + hf * 8;
;             const u32x4 rc = *(const u32x4*)(prow + o_), kc = kcs[hf], vc = *(const u32x4*)(prow + 1024 + o_);
;             u32x4 rp = *(const u32x4*)(pprev + o_), vp = *(const u32x4*)(pprev + 1024 + o_); const u32x4 kp = kps[hf];
;             if (first) { rp = (u32x4){0u, 0u, 0u, 0u}; vp = rp; }
; #pragma unroll
;             for (int i2 = 0; i2 < 2; ++i2) {
;                 const int i = 2 * hf + i2, c = h * 64 + i * 16 + 4 * fq;
;                 const f32x4 mur = *(const LAS f32x4*)(PRM + c), muk = *(const LAS f32x4*)(PRM + 512 + c), muv = *(const LAS f32x4*)(PRM + 1024 + c);
;                 const f32x4 w04 = *(const LAS f32x4*)(PRM + 1536 + c), a04 = *(const LAS f32x4*)(PRM + 2048 + c), kk4 = *(const LAS f32x4*)(PRM + 2560 + c), ka4 = *(const LAS f32x4*)(PRM + 3072 + c), rk4 = *(const LAS f32x4*)(PRM + 3584 + c);
; #pragma unroll
;                 for (int j = 0; j < 4; ++j) {
	v_add_f32_e32 v36, v36, v37
	ds_bpermute_b32 v37, v2, v36
	v_add_f32_e32 v24, 1.0, v24
	v_rcp_f32_e32 v24, v24
	v_add_f32_e32 v130, -1.0, v190
	v_fma_f32 v167, v231, v130, 1.0
	s_waitcnt lgkmcnt(0)
	v_add_f32_e32 v36, v36, v37
	v_mul_f32_e32 v37, 0x4f800000, v36
	v_cmp_gt_f32_e32 vcc, s29, v36
	v_mul_f32_e32 v132, 0xbf1b4598, v24
	v_add_f32_e32 v24, 1.0, v28
	v_cndmask_b32_e32 v70, v36, v37, vcc
	v_sqrt_f32_e32 v74, v70
	v_add_u32_e32 v38, 0x108c0, v187
	v_add_u32_e32 v39, 0x118c0, v187
	ds_read_b128 v[40:43], v38
	ds_read_b128 v[36:39], v39
	v_add_u32_e32 v28, -1, v74
	v_fma_f32 v130, -v28, v74, v70
	v_cmp_ge_f32_e64 s[8:9], 0, v130
	v_add_u32_e32 v130, 1, v74
	v_add_f32_e32 v26, v26, v72
	v_cndmask_b32_e64 v28, v74, v28, s[8:9]
	v_fma_f32 v74, -v130, v74, v70
	v_cmp_lt_f32_e64 s[8:9], 0, v74
	v_add_f32_e32 v27, v27, v73
	v_mov_b32_e32 v185, v162
	v_cndmask_b32_e64 v28, v28, v130, s[8:9]
	v_mul_f32_e32 v74, 0x37800000, v28
	v_cndmask_b32_e32 v28, v28, v74, vcc
	v_cmp_class_f32_e32 vcc, v70, v223
	v_mov_b32_e32 v191, v163
	v_mov_b32_e32 v163, v90
	v_cndmask_b32_e32 v28, v28, v70, vcc
	v_max_f32_e32 v70, 0x2b8cbccc, v28
	v_div_scale_f32 v74, s[8:9], v70, v70, 1.0
	v_rcp_f32_e32 v130, v74
	v_rcp_f32_e32 v28, v24
	v_add_f32_e32 v24, v25, v71
	v_mul_f32_e32 v150, 0xbfb8aa3b, v24
	v_fma_f32 v24, -v74, v130, 1.0
	v_fmac_f32_e32 v130, v24, v130
	v_div_scale_f32 v24, vcc, 1.0, v70, 1.0
	v_mul_f32_e32 v25, v24, v130
	v_fma_f32 v71, -v74, v25, v24
	v_fmac_f32_e32 v25, v71, v130
	v_fma_f32 v24, -v74, v25, v24
	v_div_fmas_f32 v24, v24, v130, v25
	v_div_fixup_f32 v130, v24, v70, 1.0
	v_pk_mul_f32 v[24:25], v[228:229], v[130:131] op_sel_hi:[1,0]
	v_pk_mul_f32 v[70:71], v[188:189], v[130:131] op_sel_hi:[1,0]
	v_pk_mul_f32 v[188:189], v[202:203], v[130:131] op_sel_hi:[1,0]
	v_pk_mul_f32 v[202:203], v[232:233], v[130:131] op_sel_hi:[1,0]
	v_pk_mul_f32 v[172:173], v[170:171], v[24:25]
	v_pk_mul_f32 v[176:177], v[176:177], v[70:71]
	v_pk_mul_f32 v[182:183], v[188:189], v[182:183]
	v_pk_mul_f32 v[196:197], v[202:203], v[196:197]
	v_cvt_pk_f16_f32 v231, v202, v203
	v_cvt_pk_f16_f32 v230, v188, v189
	v_cvt_pk_f16_f32 v229, v70, v71
	v_cvt_pk_f16_f32 v228, v24, v25
	v_cvt_pk_f16_f32 v168, v172, v173
	v_cvt_pk_f16_f32 v169, v176, v177
	v_cvt_pk_f16_f32 v170, v182, v183
	v_cvt_pk_f16_f32 v171, v196, v197
	s_waitcnt vmcnt(0)
	v_mov_b64_e32 v[232:233], v[114:115]
	v_mov_b64_e32 v[234:235], v[116:117]
	v_mov_b64_e32 v[70:71], v[106:107]
	v_mov_b64_e32 v[72:73], v[108:109]
	v_mov_b64_e32 v[114:115], v[228:229]
	v_mov_b64_e32 v[116:117], v[230:231]
	v_mov_b64_e32 v[106:107], v[168:169]
	v_mov_b64_e32 v[108:109], v[170:171]
	v_mov_b64_e32 v[168:169], v[98:99]
	v_mov_b64_e32 v[170:171], v[100:101]
	v_mov_b64_e32 v[228:229], v[102:103]
	v_mov_b64_e32 v[230:231], v[104:105]
	s_nop 0
	v_mov_b32_e32 v162, v172
	v_mul_f32_e32 v90, v86, v90
	v_mul_f32_e32 v25, 0x3fb8aa3b, v132
	v_fma_f32 v132, v32, v90, 0
	v_mov_b32_e32 v90, v173
	v_mul_f32_e32 v32, v87, v91
	v_pk_fma_f32 v[162:163], v[86:87], v[162:163], 0 op_sel_hi:[0,1,0]
	v_fmac_f32_e32 v132, v33, v32
	v_mov_b32_e32 v32, v176
	v_mov_b32_e32 v33, v88
	v_mul_f32_e32 v88, v82, v88
	v_pk_fma_f32 v[86:87], v[86:87], v[90:91], v[162:163] op_sel:[1,0,0]
	v_fmac_f32_e32 v132, v34, v88
	v_mov_b32_e32 v88, v177
	v_mul_f32_e32 v34, v83, v89
	v_pk_fma_f32 v[32:33], v[82:83], v[32:33], v[86:87] op_sel_hi:[0,1,1]
	v_exp_f32_e32 v24, v150
	v_fmac_f32_e32 v132, v35, v34
	v_mov_b32_e32 v34, v182
	v_mov_b32_e32 v35, v174
	v_mul_f32_e32 v150, v92, v174
	v_pk_fma_f32 v[32:33], v[82:83], v[88:89], v[32:33] op_sel:[1,0,0]
	v_fmac_f32_e32 v132, v46, v150
	v_mov_b32_e32 v174, v183
	v_mul_f32_e32 v46, v93, v175
	v_pk_fma_f32 v[32:33], v[92:93], v[34:35], v[32:33] op_sel_hi:[0,1,1]
	v_fmac_f32_e32 v132, v47, v46
	v_mov_b32_e32 v46, v196
	v_mov_b32_e32 v47, v180
	v_mul_f32_e32 v150, v84, v180
	v_pk_fma_f32 v[32:33], v[92:93], v[174:175], v[32:33] op_sel:[1,0,0]
	v_add_f32_e32 v29, v29, v75
	v_fmac_f32_e32 v132, v48, v150
	v_pk_fma_f32 v[32:33], v[84:85], v[46:47], v[32:33] op_sel_hi:[0,1,1]
	v_mov_b32_e32 v180, v197
	v_mul_f32_e32 v34, v85, v181
	v_mul_f32_e32 v29, 0xbfb8aa3b, v29
	v_fmac_f32_e32 v132, v49, v34
	v_pk_fma_f32 v[34:35], v[84:85], v[180:181], v[32:33] op_sel:[1,0,0]
	v_pk_mul_f32 v[32:33], v[178:179], v[130:131] op_sel_hi:[1,0]
	v_exp_f32_e32 v29, v29
	v_mov_b32_e32 v46, v32
	v_mov_b32_e32 v47, v192
	v_mov_b32_e32 v187, v193
	v_pk_mul_f32 v[82:83], v[46:47], v[186:187]
	v_add_f32_e32 v24, 1.0, v24
	v_exp_f32_e32 v74, v25
	v_add_f32_e32 v25, -1.0, v28
	v_rcp_f32_e32 v24, v24
	v_mov_b32_e32 v200, v33
	v_fma_f32 v155, v58, v25, 1.0
	v_add_f32_e32 v25, 1.0, v29
	v_pk_mul_f32 v[84:85], v[200:201], v[160:161]
	v_rcp_f32_e32 v58, v25
	v_mul_f32_e32 v24, 0xbf1b4598, v24
	v_mul_f32_e32 v24, 0x3fb8aa3b, v24
	v_exp_f32_e32 v75, v24
	v_add_f32_e32 v24, -1.0, v58
	v_fma_f32 v153, v59, v24, 1.0
	v_cvt_pk_f16_f32 v24, v78, v79
	v_cvt_pk_f16_f32 v32, v32, v33
	v_mul_f32_e32 v26, 0xbfb8aa3b, v26
	v_mul_f32_e32 v27, 0xbfb8aa3b, v27
	v_exp_f32_e32 v26, v26
	v_exp_f32_e32 v27, v27
	v_mov_b32_e32 v29, v164
	v_mov_b32_e32 v59, v165
	v_add_f32_e32 v26, 1.0, v26
	v_add_f32_e32 v25, 1.0, v27
	v_rcp_f32_e32 v26, v26
	v_rcp_f32_e32 v25, v25
	v_pk_fma_f32 v[22:23], v[22:23], v[44:45], s[0:1]
	v_pk_mov_b32 v[20:21], v[20:21], v[30:31] op_sel:[1,0]
	v_mul_f32_e32 v26, 0xbf1b4598, v26
	v_mul_f32_e32 v25, 0xbf1b4598, v25
	v_mov_b32_e32 v22, v151
	s_nop 0
	v_cndmask_b32_e64 v49, v168, 0, s[6:7]
	v_lshlrev_b32_e32 v48, 16, v49
	s_nop 0
	v_lshlrev_b32_e32 v46, 16, v232
	v_and_b32_e32 v47, 0xffff0000, v232
	v_and_b32_e32 v49, 0xffff0000, v49
; #define LAS __attribute__((address_space(3)))
; __device__ __forceinline__ float fast_sigmoid(float x) { return __builtin_amdgcn_rcpf(1.f + __expf(-x)); }
; __device__ __forceinline__ void prep_rwkv_phase(const Params& p, LAS unsigned char* lds, int gw, int ngw, int wave, int lane) {
;     ...
;         for (int hf = 0; hf < 2; ++hf) {
;             h16x8 owr, odec, ok2, ov, okk, ob;
;             const int o_ = h * 64 + fq * 16 + hf * 8;
;             const u32x4 rc = *(const u32x4*)(prow + o_), kc = kcs[hf], vc = *(const u32x4*)(prow + 1024 + o_);
;             u32x4 rp = *(const u32x4*)(pprev + o_), vp = *(const u32x4*)(pprev + 1024 + o_); const u32x4 kp = kps[hf];
;             if (first) { rp = (u32x4){0u, 0u, 0u, 0u}; vp = rp; }
; #pragma unroll
;             for (int i2 = 0; i2 < 2; ++i2) {
;                 const int i = 2 * hf + i2, c = h * 64 + i * 16 + 4 * fq;
;                 const f32x4 mur = *(const LAS f32x4*)(PRM + c), muk = *(const LAS f32x4*)(PRM + 512 + c), muv = *(const LAS f32x4*)(PRM + 1024 + c);
;                 const f32x4 w04 = *(const LAS f32x4*)(PRM + 1536 + c), a04 = *(const LAS f32x4*)(PRM + 2048 + c), kk4 = *(const LAS f32x4*)(PRM + 2560 + c), ka4 = *(const LAS f32x4*)(PRM + 3072 + c), rk4 = *(const LAS f32x4*)(PRM + 3584 + c);
; #pragma unroll
;                 for (int j = 0; j < 4; ++j) {
;                     const int e8 = i2 * 4 + j, e = hf * 8 + e8; const unsigned wsel = (e8 >> 1); const bool hiw = e8 & 1;
;     ...
;                     const float rcur = PREP_GET(rc), rprv = PREP_GET(rp), kcur = PREP_GET(kc), kprv = PREP_GET(kp), vcur = PREP_GET(vc), vprv = PREP_GET(vp);
;     ...
;                     const float r = rcur + (rprv - rcur) * mur[j], k = kcur + (kprv - kcur) * muk[j], v = vcur + (vprv - vcur) * muv[j];
;                     const float dec = __expf(-0.60653066f * fast_sigmoid(w04[j] + accD[i][j]));
;                     const float a = fast_sigmoid(a04[j] + accA[i][j]);
;                     const float kraw = k * kk4[j], k2 = k * (1.f + (a - 1.f) * ka4[j]);
;                     const float kkn = kraw * inv, bn = kkn * a; sbr += bn * r; skr += k2 * r; sbo += r * k2 * rk4[j];
;                     okk[e8] = (h16)kkn; ob[e8] = (h16)bn;
;                     owr[e8] = (h16)(dec * r); odec[e8] = (h16)dec; ok2[e8] = (h16)k2; ov[e8] = (h16)v;
;                 }
;             }
	v_pk_add_f32 v[48:49], v[48:49], v[46:47] neg_lo:[0,1] neg_hi:[0,1]
	v_cndmask_b32_e64 v89, v228, 0, s[6:7]
	v_pk_fma_f32 v[48:49], v[62:63], v[48:49], v[46:47]
	v_cndmask_b32_e64 v92, v169, 0, s[6:7]
	v_pk_mul_f32 v[46:47], v[48:49], v[82:83] op_sel_hi:[0,1]
	v_pk_fma_f32 v[34:35], v[48:49], v[82:83], v[34:35] op_sel_hi:[0,1,1]
	v_fmac_f32_e32 v132, v66, v47
	v_pk_mul_f32 v[62:63], v[48:49], v[84:85]
	v_pk_mul_f32 v[46:47], v[48:49], v[78:79]
	v_pk_fma_f32 v[34:35], v[48:49], v[84:85], v[34:35] op_sel:[1,0,0]
	v_fmac_f32_e32 v132, v67, v63
	s_nop 0
	v_lshlrev_b32_e32 v48, 16, v70
	v_and_b32_e32 v49, 0xffff0000, v70
	v_lshlrev_b32_e32 v62, 16, v89
	v_and_b32_e32 v63, 0xffff0000, v89
	v_pk_add_f32 v[62:63], v[62:63], v[48:49] neg_lo:[0,1] neg_hi:[0,1]
	v_lshlrev_b32_e32 v78, 16, v92
	v_pk_fma_f32 v[48:49], v[50:51], v[62:63], v[48:49]
	v_and_b32_e32 v79, 0xffff0000, v92
	v_cvt_pk_f16_f32 v50, v48, v49
	v_pk_mul_f32 v[48:49], v[158:159], v[130:131] op_sel_hi:[1,0]
	v_cndmask_b32_e64 v88, v229, 0, s[6:7]
	v_mov_b32_e32 v194, v48
	v_cvt_pk_f16_f32 v33, v48, v49
	v_mov_b32_e32 v166, v49
	v_lshlrev_b32_e32 v48, 16, v233
	v_and_b32_e32 v49, 0xffff0000, v233
	v_pk_add_f32 v[78:79], v[78:79], v[48:49] neg_lo:[0,1] neg_hi:[0,1]
	v_pk_mul_f32 v[62:63], v[194:195], v[184:185]
	v_pk_fma_f32 v[48:49], v[64:65], v[78:79], v[48:49]
	v_pk_mul_f32 v[66:67], v[166:167], v[190:191]
	v_pk_mul_f32 v[64:65], v[48:49], v[62:63] op_sel_hi:[0,1]
	v_fmac_f32_e32 v132, v68, v65
	v_pk_mul_f32 v[64:65], v[48:49], v[80:81]
	v_cvt_pk_f16_f32 v46, v46, v47
	v_pk_fma_f32 v[34:35], v[48:49], v[62:63], v[34:35] op_sel_hi:[0,1,1]
	v_cvt_pk_f16_f32 v47, v64, v65
	v_pk_mul_f32 v[64:65], v[48:49], v[66:67]
	v_pk_fma_f32 v[48:49], v[48:49], v[66:67], v[34:35] op_sel:[1,0,0]
	v_fmac_f32_e32 v132, v69, v65
	v_lshlrev_b32_e32 v34, 16, v71
	v_and_b32_e32 v35, 0xffff0000, v71
	v_lshlrev_b32_e32 v64, 16, v88
	v_and_b32_e32 v65, 0xffff0000, v88
	v_pk_add_f32 v[64:65], v[64:65], v[34:35] neg_lo:[0,1] neg_hi:[0,1]
	v_cndmask_b32_e64 v91, v170, 0, s[6:7]
	v_pk_fma_f32 v[34:35], v[52:53], v[64:65], v[34:35]
	v_lshlrev_b32_e32 v52, 16, v234
	v_cvt_pk_f16_f32 v51, v34, v35
	v_pk_mul_f32 v[34:35], v[156:157], v[130:131] op_sel_hi:[1,0]
	v_and_b32_e32 v53, 0xffff0000, v234
	v_lshlrev_b32_e32 v64, 16, v91
	v_and_b32_e32 v65, 0xffff0000, v91
	v_mov_b32_e32 v154, v34
	v_pk_add_f32 v[64:65], v[64:65], v[52:53] neg_lo:[0,1] neg_hi:[0,1]
	v_pk_mul_f32 v[28:29], v[154:155], v[28:29]
	v_mov_b32_e32 v152, v35
	s_waitcnt lgkmcnt(1)
	v_pk_fma_f32 v[40:41], v[64:65], v[40:41], v[52:53]
	v_pk_mul_f32 v[58:59], v[152:153], v[58:59]
	v_pk_mul_f32 v[52:53], v[40:41], v[28:29] op_sel_hi:[0,1]
	v_cndmask_b32_e64 v87, v230, 0, s[6:7]
	v_fmac_f32_e32 v132, v54, v53
	v_pk_mul_f32 v[52:53], v[40:41], v[58:59]
	v_lshlrev_b32_e32 v54, 16, v87
	v_fmac_f32_e32 v132, v55, v53
	v_lshlrev_b32_e32 v52, 16, v72
	v_and_b32_e32 v53, 0xffff0000, v72
	v_and_b32_e32 v55, 0xffff0000, v87
	v_pk_add_f32 v[54:55], v[54:55], v[52:53] neg_lo:[0,1] neg_hi:[0,1]
	v_mul_f32_e32 v26, 0x3fb8aa3b, v26
	s_waitcnt lgkmcnt(0)
	v_pk_fma_f32 v[36:37], v[54:55], v[36:37], v[52:53]
	v_mul_f32_e32 v25, 0x3fb8aa3b, v25
	v_cvt_pk_f16_f32 v52, v36, v37
	v_pk_mul_f32 v[36:37], v[60:61], v[130:131]
	v_cndmask_b32_e64 v90, v171, 0, s[6:7]
	v_mov_b32_e32 v37, v23
	v_mov_b32_e32 v23, v44
	v_pk_mul_f32 v[44:45], v[36:37], v[22:23]
	v_pk_mul_f32 v[22:23], v[198:199], v[130:131]
	v_pk_fma_f32 v[54:55], v[76:77], v[30:31], s[0:1]
	v_exp_f32_e32 v188, v26
	v_exp_f32_e32 v189, v25
	v_cvt_pk_f16_f32 v34, v34, v35
	v_mov_b32_e32 v23, v55
	v_cvt_pk_f16_f32 v35, v36, v22
	v_lshlrev_b32_e32 v36, 16, v235
	v_and_b32_e32 v37, 0xffff0000, v235
	v_lshlrev_b32_e32 v54, 16, v90
	v_and_b32_e32 v55, 0xffff0000, v90
	v_pk_add_f32 v[54:55], v[54:55], v[36:37] neg_lo:[0,1] neg_hi:[0,1]
	v_pk_fma_f32 v[64:65], v[40:41], v[28:29], v[48:49] op_sel_hi:[0,1,1]
	v_pk_fma_f32 v[36:37], v[54:55], v[42:43], v[36:37]
	v_pk_mul_f32 v[48:49], v[40:41], v[74:75]
	v_pk_mul_f32 v[42:43], v[36:37], v[44:45] op_sel_hi:[0,1]
	v_pk_fma_f32 v[40:41], v[40:41], v[58:59], v[64:65] op_sel:[1,0,0]
	v_pk_mul_f32 v[30:31], v[22:23], v[20:21]
	v_fmac_f32_e32 v132, v56, v43
	v_pk_mul_f32 v[42:43], v[36:37], v[188:189]
	v_cndmask_b32_e64 v86, v231, 0, s[6:7]
	v_cvt_pk_f16_f32 v48, v48, v49
	v_pk_fma_f32 v[40:41], v[36:37], v[44:45], v[40:41] op_sel_hi:[0,1,1]
	v_cvt_pk_f16_f32 v49, v42, v43
	v_pk_mul_f32 v[42:43], v[36:37], v[30:31]
	v_cvt_pk_f16_f32 v23, v44, v30
	v_cvt_pk_f16_f32 v22, v28, v58
	v_pk_fma_f32 v[36:37], v[36:37], v[30:31], v[40:41] op_sel:[1,0,0]
	v_fmac_f32_e32 v132, v57, v43
	v_cvt_pk_f16_f32 v43, v45, v31
	v_cvt_pk_f16_f32 v42, v29, v59
	v_lshlrev_b32_e32 v28, 16, v73
	v_and_b32_e32 v29, 0xffff0000, v73
	v_lshlrev_b32_e32 v30, 16, v86
	v_and_b32_e32 v31, 0xffff0000, v86
	v_pk_add_f32 v[30:31], v[30:31], v[28:29] neg_lo:[0,1] neg_hi:[0,1]
	v_cvt_pk_f16_f32 v21, v62, v66
	v_pk_fma_f32 v[28:29], v[30:31], v[38:39], v[28:29]
	ds_bpermute_b32 v30, v145, v36
	ds_bpermute_b32 v31, v145, v37
	v_cvt_pk_f16_f32 v53, v28, v29
	ds_bpermute_b32 v28, v145, v132
	v_cvt_pk_f16_f32 v20, v82, v84
	v_mbcnt_lo_u32_b32 v118, -1, 0
	v_mbcnt_hi_u32_b32 v118, -1, v118
	v_and_b32_e32 v118, 8, v118
	v_mul_i32_i24_e32 v96, 0xfffffd02, v118
	v_add_u32_e32 v96, 0xc00, v96
	v_ashrrev_i32_e32 v120, 31, v96
	v_add_co_u32_e64 v94, s[100:101], v0, v96
	s_nop 1
	v_addc_co_u32_e64 v95, s[100:101], v1, v120, s[100:101]
	v_mov_b32_dpp v98, v20 row_ror:8 row_mask:0xf bank_mask:0xf
	v_mov_b32_dpp v99, v21 row_ror:8 row_mask:0xf bank_mask:0xf
	v_mov_b32_dpp v100, v22 row_ror:8 row_mask:0xf bank_mask:0xf
	v_mov_b32_dpp v101, v23 row_ror:8 row_mask:0xf bank_mask:0xf
	v_mov_b32_dpp v20, v106 row_ror:8 row_mask:0xf bank_mask:0x3
	v_mov_b32_dpp v21, v107 row_ror:8 row_mask:0xf bank_mask:0x3
	v_mov_b32_dpp v22, v108 row_ror:8 row_mask:0xf bank_mask:0x3
	v_mov_b32_dpp v23, v109 row_ror:8 row_mask:0xf bank_mask:0x3
	v_mov_b32_dpp v106, v98 quad_perm:[0,1,2,3] row_mask:0xf bank_mask:0xc
	v_mov_b32_dpp v107, v99 quad_perm:[0,1,2,3] row_mask:0xf bank_mask:0xc
	v_mov_b32_dpp v108, v100 quad_perm:[0,1,2,3] row_mask:0xf bank_mask:0xc
	v_mov_b32_dpp v109, v101 quad_perm:[0,1,2,3] row_mask:0xf bank_mask:0xc
	global_store_dwordx4 v[94:95], v[106:109], off offset:-3072
	global_store_dwordx4 v[94:95], v[20:23], off offset:3072
	v_cvt_pk_f16_f32 v27, v188, v189
	v_cvt_pk_f16_f32 v26, v74, v75
	s_waitcnt lgkmcnt(1)
; __device__ __forceinline__ void prep_rwkv_phase(const Params& p, LAS unsigned char* lds, int gw, int ngw, int wave, int lane) {
;     ...
;             *(h16x8*)(scp + 0 * 64 + hf * 8) = okk; *(h16x8*)(scp + 3 * 64 + hf * 8) = ob; *(h16x8*)(scp + 1 * 64 + hf * 8) = owr; *(h16x8*)(scp + 2 * 64 + hf * 8) = odec; *(h16x8*)(scp + 4 * 64 + hf * 8) = ok2; *(h16x8*)(scp + 5 * 64 + hf * 8) = ov;
;         }
;         sbr += __shfl_xor(sbr, 16); sbr += __shfl_xor(sbr, 32); skr += __shfl_xor(skr, 16); skr += __shfl_xor(skr, 32); sbo += __shfl_xor(sbo, 16); sbo += __shfl_xor(sbo, 32);
;         if (fq == 0) *(f32x4*)(SS + ((size_t)(b * 8 + h) * SEQ + tin) * 4) = (f32x4){sbr, skr, sbo, 0.f};
	v_pk_add_f32 v[20:21], v[36:37], v[30:31]
	s_waitcnt lgkmcnt(0)
	v_add_f32_e32 v28, v132, v28
	ds_bpermute_b32 v22, v2, v20
	ds_bpermute_b32 v23, v2, v21
	ds_bpermute_b32 v2, v2, v28
	v_cvt_pk_f16_f32 v25, v80, v81
	v_cvt_pk_f16_f32 v41, v63, v67
	v_cvt_pk_f16_f32 v40, v83, v85
	s_nop 1
	v_mov_b32_dpp v98, v32 row_ror:8 row_mask:0xf bank_mask:0xf
	v_mov_b32_dpp v99, v33 row_ror:8 row_mask:0xf bank_mask:0xf
	v_mov_b32_dpp v100, v34 row_ror:8 row_mask:0xf bank_mask:0xf
	v_mov_b32_dpp v101, v35 row_ror:8 row_mask:0xf bank_mask:0xf
	v_mov_b32_dpp v32, v114 row_ror:8 row_mask:0xf bank_mask:0x3
	v_mov_b32_dpp v33, v115 row_ror:8 row_mask:0xf bank_mask:0x3
	v_mov_b32_dpp v34, v116 row_ror:8 row_mask:0xf bank_mask:0x3
	v_mov_b32_dpp v35, v117 row_ror:8 row_mask:0xf bank_mask:0x3
	v_mov_b32_dpp v114, v98 quad_perm:[0,1,2,3] row_mask:0xf bank_mask:0xc
	v_mov_b32_dpp v115, v99 quad_perm:[0,1,2,3] row_mask:0xf bank_mask:0xc
	v_mov_b32_dpp v116, v100 quad_perm:[0,1,2,3] row_mask:0xf bank_mask:0xc
	v_mov_b32_dpp v117, v101 quad_perm:[0,1,2,3] row_mask:0xf bank_mask:0xc
	global_store_dwordx4 v[94:95], v[114:117], off offset:-3456
	global_store_dwordx4 v[94:95], v[32:35], off offset:2688
	s_nop 1
	v_mov_b32_dpp v98, v46 row_ror:8 row_mask:0xf bank_mask:0xf
	v_mov_b32_dpp v99, v47 row_ror:8 row_mask:0xf bank_mask:0xf
	v_mov_b32_dpp v100, v48 row_ror:8 row_mask:0xf bank_mask:0xf
	v_mov_b32_dpp v101, v49 row_ror:8 row_mask:0xf bank_mask:0xf
	v_mov_b32_dpp v46, v110 row_ror:8 row_mask:0xf bank_mask:0x3
	v_mov_b32_dpp v47, v111 row_ror:8 row_mask:0xf bank_mask:0x3
	v_mov_b32_dpp v48, v112 row_ror:8 row_mask:0xf bank_mask:0x3
	v_mov_b32_dpp v49, v113 row_ror:8 row_mask:0xf bank_mask:0x3
	v_mov_b32_dpp v110, v98 quad_perm:[0,1,2,3] row_mask:0xf bank_mask:0xc
	v_mov_b32_dpp v111, v99 quad_perm:[0,1,2,3] row_mask:0xf bank_mask:0xc
	v_mov_b32_dpp v112, v100 quad_perm:[0,1,2,3] row_mask:0xf bank_mask:0xc
	v_mov_b32_dpp v113, v101 quad_perm:[0,1,2,3] row_mask:0xf bank_mask:0xc
	global_store_dwordx4 v[94:95], v[110:113], off offset:-3328
	global_store_dwordx4 v[94:95], v[46:49], off offset:2816
	s_nop 1
	v_mov_b32_dpp v98, v24 row_ror:8 row_mask:0xf bank_mask:0xf
	v_mov_b32_dpp v99, v25 row_ror:8 row_mask:0xf bank_mask:0xf
	v_mov_b32_dpp v100, v26 row_ror:8 row_mask:0xf bank_mask:0xf
	v_mov_b32_dpp v101, v27 row_ror:8 row_mask:0xf bank_mask:0xf
	v_mov_b32_dpp v24, v122 row_ror:8 row_mask:0xf bank_mask:0x3
	v_mov_b32_dpp v25, v123 row_ror:8 row_mask:0xf bank_mask:0x3
	v_mov_b32_dpp v26, v124 row_ror:8 row_mask:0xf bank_mask:0x3
	v_mov_b32_dpp v27, v125 row_ror:8 row_mask:0xf bank_mask:0x3
	v_mov_b32_dpp v122, v98 quad_perm:[0,1,2,3] row_mask:0xf bank_mask:0xc
	v_mov_b32_dpp v123, v99 quad_perm:[0,1,2,3] row_mask:0xf bank_mask:0xc
	v_mov_b32_dpp v124, v100 quad_perm:[0,1,2,3] row_mask:0xf bank_mask:0xc
	v_mov_b32_dpp v125, v101 quad_perm:[0,1,2,3] row_mask:0xf bank_mask:0xc
	global_store_dwordx4 v[94:95], v[122:125], off offset:-3200
	global_store_dwordx4 v[94:95], v[24:27], off offset:2944
	s_nop 1
	v_mov_b32_dpp v98, v40 row_ror:8 row_mask:0xf bank_mask:0xf
	v_mov_b32_dpp v99, v41 row_ror:8 row_mask:0xf bank_mask:0xf
	v_mov_b32_dpp v100, v42 row_ror:8 row_mask:0xf bank_mask:0xf
	v_mov_b32_dpp v101, v43 row_ror:8 row_mask:0xf bank_mask:0xf
	v_mov_b32_dpp v40, v126 row_ror:8 row_mask:0xf bank_mask:0x3
	v_mov_b32_dpp v41, v127 row_ror:8 row_mask:0xf bank_mask:0x3
	v_mov_b32_dpp v42, v128 row_ror:8 row_mask:0xf bank_mask:0x3
	v_mov_b32_dpp v43, v129 row_ror:8 row_mask:0xf bank_mask:0x3
	v_mov_b32_dpp v126, v98 quad_perm:[0,1,2,3] row_mask:0xf bank_mask:0xc
	v_mov_b32_dpp v127, v99 quad_perm:[0,1,2,3] row_mask:0xf bank_mask:0xc
	v_mov_b32_dpp v128, v100 quad_perm:[0,1,2,3] row_mask:0xf bank_mask:0xc
	v_mov_b32_dpp v129, v101 quad_perm:[0,1,2,3] row_mask:0xf bank_mask:0xc
	global_store_dwordx4 v[94:95], v[126:129], off offset:-2944
	global_store_dwordx4 v[94:95], v[40:43], off offset:3200
	s_nop 1
	v_mov_b32_dpp v98, v50 row_ror:8 row_mask:0xf bank_mask:0xf
	v_mov_b32_dpp v99, v51 row_ror:8 row_mask:0xf bank_mask:0xf
	v_mov_b32_dpp v100, v52 row_ror:8 row_mask:0xf bank_mask:0xf
	v_mov_b32_dpp v101, v53 row_ror:8 row_mask:0xf bank_mask:0xf
	v_mov_b32_dpp v50, v240 row_ror:8 row_mask:0xf bank_mask:0x3
	v_mov_b32_dpp v51, v241 row_ror:8 row_mask:0xf bank_mask:0x3
	v_mov_b32_dpp v52, v242 row_ror:8 row_mask:0xf bank_mask:0x3
	v_mov_b32_dpp v53, v243 row_ror:8 row_mask:0xf bank_mask:0x3
	v_mov_b32_dpp v240, v98 quad_perm:[0,1,2,3] row_mask:0xf bank_mask:0xc
	v_mov_b32_dpp v241, v99 quad_perm:[0,1,2,3] row_mask:0xf bank_mask:0xc
	v_mov_b32_dpp v242, v100 quad_perm:[0,1,2,3] row_mask:0xf bank_mask:0xc
	v_mov_b32_dpp v243, v101 quad_perm:[0,1,2,3] row_mask:0xf bank_mask:0xc
	global_store_dwordx4 v[94:95], v[240:243], off offset:-2816
	global_store_dwordx4 v[94:95], v[50:53], off offset:3328
	s_and_saveexec_b64 s[8:9], s[4:5]
	s_cbranch_execz .LBB0_860
	v_lshl_add_u64 v[24:25], s[92:93], 0, v[138:139]
	s_waitcnt lgkmcnt(1)
	v_pk_add_f32 v[0:1], v[20:21], v[22:23]
	s_waitcnt lgkmcnt(0)
	v_add_f32_e32 v2, v28, v2
	global_store_dwordx4 v[24:25], v[0:3], off
